# GU main loop: leading wave half (wr=0) waits for LDS-DMA pieces at the end of its MMA segment instead of in the load segment
# baseline (speedup 1.0000x reference)
.LBB0_942:
	s_ashr_i32 s27, s26, 31
	s_lshl_b64 s[28:29], s[26:27], 20
	s_add_u32 s28, s14, s28
	s_addc_u32 s29, s15, s29
	s_and_b64 s[30:31], s[38:39], exec
	s_cselect_b32 s17, s29, s37
	s_cselect_b32 s27, s28, s36
	s_ashr_i32 s25, s24, 31
	s_lshl_b64 s[30:31], s[24:25], 20
	s_add_u32 s30, s6, s30
	s_addc_u32 s31, s7, s31
	s_and_b64 s[40:41], s[38:39], exec
	s_cselect_b32 s25, s31, s5
	s_cselect_b32 s49, s30, s4
	s_add_u32 s50, s4, 0x100
	s_addc_u32 s51, s5, 0
	s_add_u32 s36, s36, 0x80080
	v_mov_b32_e32 v0, 0
	s_addc_u32 s37, s37, 0
	s_mov_b32 s52, -2
	v_mov_b32_e32 v1, v0
	v_mov_b32_e32 v2, v0
	v_mov_b32_e32 v3, v0
	v_mov_b32_e32 v14, v0
	v_mov_b32_e32 v15, v0
	v_mov_b32_e32 v16, v0
	v_mov_b32_e32 v17, v0
	v_mov_b32_e32 v22, v0
	v_mov_b32_e32 v23, v0
	v_mov_b32_e32 v24, v0
	v_mov_b32_e32 v25, v0
	v_mov_b32_e32 v30, v0
	v_mov_b32_e32 v31, v0
	v_mov_b32_e32 v32, v0
	v_mov_b32_e32 v33, v0
	v_mov_b32_e32 v38, v0
	v_mov_b32_e32 v39, v0
	v_mov_b32_e32 v40, v0
	v_mov_b32_e32 v41, v0
	v_mov_b32_e32 v46, v0
	v_mov_b32_e32 v47, v0
	v_mov_b32_e32 v48, v0
	v_mov_b32_e32 v49, v0
	v_mov_b32_e32 v54, v0
	v_mov_b32_e32 v55, v0
	v_mov_b32_e32 v56, v0
	v_mov_b32_e32 v57, v0
	v_mov_b32_e32 v62, v0
	v_mov_b32_e32 v63, v0
	v_mov_b32_e32 v64, v0
	v_mov_b32_e32 v65, v0
	v_mov_b32_e32 v4, v0
	v_mov_b32_e32 v5, v0
	v_mov_b32_e32 v6, v0
	v_mov_b32_e32 v7, v0
	v_mov_b32_e32 v10, v0
	v_mov_b32_e32 v11, v0
	v_mov_b32_e32 v12, v0
	v_mov_b32_e32 v13, v0
	v_mov_b32_e32 v18, v0
	v_mov_b32_e32 v19, v0
	v_mov_b32_e32 v20, v0
	v_mov_b32_e32 v21, v0
	v_mov_b32_e32 v26, v0
	v_mov_b32_e32 v27, v0
	v_mov_b32_e32 v28, v0
	v_mov_b32_e32 v29, v0
	v_mov_b32_e32 v34, v0
	v_mov_b32_e32 v35, v0
	v_mov_b32_e32 v36, v0
	v_mov_b32_e32 v37, v0
	v_mov_b32_e32 v42, v0
	v_mov_b32_e32 v43, v0
	v_mov_b32_e32 v44, v0
	v_mov_b32_e32 v45, v0
	v_mov_b32_e32 v50, v0
	v_mov_b32_e32 v51, v0
	v_mov_b32_e32 v52, v0
	v_mov_b32_e32 v53, v0
	v_mov_b32_e32 v58, v0
	v_mov_b32_e32 v59, v0
	v_mov_b32_e32 v60, v0
	v_mov_b32_e32 v61, v0
	v_mov_b32_e32 v70, v0
	v_mov_b32_e32 v71, v0
	v_mov_b32_e32 v72, v0
	v_mov_b32_e32 v73, v0
	v_mov_b32_e32 v78, v0
	v_mov_b32_e32 v79, v0
	v_mov_b32_e32 v80, v0
	v_mov_b32_e32 v81, v0
	v_mov_b32_e32 v86, v0
	v_mov_b32_e32 v87, v0
	v_mov_b32_e32 v88, v0
	v_mov_b32_e32 v89, v0
	v_mov_b32_e32 v94, v0
	v_mov_b32_e32 v95, v0
	v_mov_b32_e32 v96, v0
	v_mov_b32_e32 v97, v0
	v_mov_b32_e32 v102, v0
	v_mov_b32_e32 v103, v0
	v_mov_b32_e32 v104, v0
	v_mov_b32_e32 v105, v0
	v_mov_b32_e32 v110, v0
	v_mov_b32_e32 v111, v0
	v_mov_b32_e32 v112, v0
	v_mov_b32_e32 v113, v0
	v_mov_b32_e32 v114, v0
	v_mov_b32_e32 v115, v0
	v_mov_b32_e32 v116, v0
	v_mov_b32_e32 v117, v0
	v_mov_b32_e32 v122, v0
	v_mov_b32_e32 v123, v0
	v_mov_b32_e32 v124, v0
	v_mov_b32_e32 v125, v0
	v_mov_b32_e32 v66, v0
	v_mov_b32_e32 v67, v0
	v_mov_b32_e32 v68, v0
	v_mov_b32_e32 v69, v0
	v_mov_b32_e32 v74, v0
	v_mov_b32_e32 v75, v0
	v_mov_b32_e32 v76, v0
	v_mov_b32_e32 v77, v0
	v_mov_b32_e32 v82, v0
	v_mov_b32_e32 v83, v0
	v_mov_b32_e32 v84, v0
	v_mov_b32_e32 v85, v0
	v_mov_b32_e32 v90, v0
	v_mov_b32_e32 v91, v0
	v_mov_b32_e32 v92, v0
	v_mov_b32_e32 v93, v0
	v_mov_b32_e32 v98, v0
	v_mov_b32_e32 v99, v0
	v_mov_b32_e32 v100, v0
	v_mov_b32_e32 v101, v0
	v_mov_b32_e32 v106, v0
	v_mov_b32_e32 v107, v0
	v_mov_b32_e32 v108, v0
	v_mov_b32_e32 v109, v0
	v_mov_b32_e32 v118, v0
	v_mov_b32_e32 v119, v0
	v_mov_b32_e32 v120, v0
	v_mov_b32_e32 v121, v0
	v_mov_b32_e32 v126, v0
	v_mov_b32_e32 v127, v0
	v_mov_b32_e32 v128, v0
	v_mov_b32_e32 v129, v0
	s_and_b64 vcc, exec, s[22:23]
	s_cbranch_vccnz .Lgu_x
.LBB0_943:
	s_add_u32 s4, s36, 0xfff80080
	s_addc_u32 s5, s37, -1
	s_add_i32 s53, 0, 0x10000
	s_cmp_eq_u32 s52, 28
	s_cselect_b32 s41, s17, s5
	s_cselect_b32 s40, s27, s4
	v_add_u32_e32 v8, s53, v178
	s_cselect_b32 s5, s25, s51
	s_cselect_b32 s4, s49, s50
	s_add_i32 s56, 0, 0x14000
	ds_read_b128 v[142:145], v8
	ds_read_b128 v[146:149], v8 offset:1024
	ds_read_b128 v[150:153], v8 offset:2048
	ds_read_b128 v[172:175], v8 offset:3072
	v_add_u32_e32 v8, s56, v178
	ds_read_b128 v[190:193], v8
	ds_read_b128 v[194:197], v8 offset:1024
	ds_read_b128 v[198:201], v8 offset:2048
	ds_read_b128 v[202:205], v8 offset:3072
	v_lshl_add_u64 v[176:177], s[36:37], 0, v[140:141]
	s_add_i32 m0, s35, 0xc000
	ds_read_b128 v[206:209], v180
	ds_read_b128 v[210:213], v180 offset:1024
	ds_read_b128 v[214:217], v180 offset:2048
	ds_read_b128 v[218:221], v180 offset:3072
	ds_read_b128 v[226:229], v180 offset:4096
	ds_read_b128 v[230:233], v180 offset:5120
	ds_read_b128 v[234:237], v180 offset:6144
	ds_read_b128 v[238:241], v180 offset:7168
	global_load_lds_dwordx4 v[176:177], off
	v_lshl_add_u64 v[176:177], s[36:37], 0, v[138:139]
	s_add_i32 m0, s35, 0xe000
	s_nop 0
	global_load_lds_dwordx4 v[176:177], off
	s_waitcnt vmcnt(8)
	s_waitcnt lgkmcnt(0)
	s_barrier
	s_setprio 1
	s_waitcnt lgkmcnt(0)
	v_mfma_f32_16x16x32_bf16 v[126:129], v[142:145], v[206:209], v[126:129]
	v_mfma_f32_16x16x32_bf16 v[118:121], v[150:153], v[206:209], v[118:121]
	v_mfma_f32_16x16x32_bf16 v[106:109], v[142:145], v[214:217], v[106:109]
	v_mfma_f32_16x16x32_bf16 v[98:101], v[150:153], v[214:217], v[98:101]
	v_mfma_f32_16x16x32_bf16 v[90:93], v[142:145], v[226:229], v[90:93]
	v_mfma_f32_16x16x32_bf16 v[82:85], v[150:153], v[226:229], v[82:85]
	v_mfma_f32_16x16x32_bf16 v[74:77], v[142:145], v[234:237], v[74:77]
	v_mfma_f32_16x16x32_bf16 v[66:69], v[150:153], v[234:237], v[66:69]
	v_mfma_f32_16x16x32_bf16 v[126:129], v[146:149], v[210:213], v[126:129]
	v_mfma_f32_16x16x32_bf16 v[118:121], v[172:175], v[210:213], v[118:121]
	v_mfma_f32_16x16x32_bf16 v[106:109], v[146:149], v[218:221], v[106:109]
	v_mfma_f32_16x16x32_bf16 v[98:101], v[172:175], v[218:221], v[98:101]
	v_mfma_f32_16x16x32_bf16 v[90:93], v[146:149], v[230:233], v[90:93]
	v_mfma_f32_16x16x32_bf16 v[82:85], v[172:175], v[230:233], v[82:85]
	v_mfma_f32_16x16x32_bf16 v[74:77], v[146:149], v[238:241], v[74:77]
	v_mfma_f32_16x16x32_bf16 v[66:69], v[172:175], v[238:241], v[66:69]
	s_setprio 0
	s_setprio 1
	v_mfma_f32_16x16x32_bf16 v[122:125], v[190:193], v[206:209], v[122:125]
	v_mfma_f32_16x16x32_bf16 v[114:117], v[198:201], v[206:209], v[114:117]
	v_mfma_f32_16x16x32_bf16 v[110:113], v[190:193], v[214:217], v[110:113]
	v_mfma_f32_16x16x32_bf16 v[102:105], v[198:201], v[214:217], v[102:105]
	v_mfma_f32_16x16x32_bf16 v[94:97], v[190:193], v[226:229], v[94:97]
	v_mfma_f32_16x16x32_bf16 v[86:89], v[198:201], v[226:229], v[86:89]
	v_mfma_f32_16x16x32_bf16 v[78:81], v[190:193], v[234:237], v[78:81]
	v_mfma_f32_16x16x32_bf16 v[70:73], v[198:201], v[234:237], v[70:73]
	v_mfma_f32_16x16x32_bf16 v[122:125], v[194:197], v[210:213], v[122:125]
	v_mfma_f32_16x16x32_bf16 v[114:117], v[202:205], v[210:213], v[114:117]
	v_mfma_f32_16x16x32_bf16 v[110:113], v[194:197], v[218:221], v[110:113]
	v_mfma_f32_16x16x32_bf16 v[102:105], v[202:205], v[218:221], v[102:105]
	v_mfma_f32_16x16x32_bf16 v[94:97], v[194:197], v[230:233], v[94:97]
	v_mfma_f32_16x16x32_bf16 v[86:89], v[202:205], v[230:233], v[86:89]
	v_mfma_f32_16x16x32_bf16 v[78:81], v[194:197], v[238:241], v[78:81]
	v_mfma_f32_16x16x32_bf16 v[70:73], v[202:205], v[238:241], v[70:73]
	s_setprio 0
	s_barrier
	s_add_i32 s53, s53, s8
	v_lshl_add_u64 v[176:177], s[4:5], 0, v[134:135]
	s_mov_b32 m0, s53
	ds_read_b128 v[206:209], v180 offset:16384
	ds_read_b128 v[210:213], v180 offset:17408
	ds_read_b128 v[214:217], v180 offset:18432
	ds_read_b128 v[218:221], v180 offset:19456
	ds_read_b128 v[226:229], v180 offset:20480
	ds_read_b128 v[230:233], v180 offset:21504
	ds_read_b128 v[234:237], v180 offset:22528
	ds_read_b128 v[238:241], v180 offset:23552
	global_load_lds_dwordx4 v[176:177], off
	s_add_i32 m0, s53, 0x2000
	s_add_u32 s54, s4, 0x80000
	v_lshl_add_u64 v[222:223], s[4:5], 0, v[130:131]
	s_addc_u32 s55, s5, 0
	s_add_i32 s53, s56, s8
	global_load_lds_dwordx4 v[222:223], off
	v_lshl_add_u64 v[242:243], s[54:55], 0, v[134:135]
	s_mov_b32 m0, s53
	v_lshl_add_u64 v[244:245], s[40:41], 0, v[132:133]
	global_load_lds_dwordx4 v[242:243], off
	v_lshl_add_u64 v[242:243], s[54:55], 0, v[130:131]
	s_add_i32 m0, s53, 0x2000
	s_nop 0
	global_load_lds_dwordx4 v[242:243], off
	v_lshl_add_u64 v[242:243], s[40:41], 0, v[136:137]
	s_mov_b32 m0, s35
	s_nop 0
	global_load_lds_dwordx4 v[242:243], off
	s_mov_b32 m0, s42
	s_nop 0
	global_load_lds_dwordx4 v[244:245], off
	s_waitcnt vmcnt(8)
	s_waitcnt lgkmcnt(0)
	s_barrier
	s_setprio 1
	s_waitcnt lgkmcnt(0)
	v_mfma_f32_16x16x32_bf16 v[58:61], v[142:145], v[206:209], v[58:61]
	v_mfma_f32_16x16x32_bf16 v[50:53], v[150:153], v[206:209], v[50:53]
	v_mfma_f32_16x16x32_bf16 v[42:45], v[142:145], v[214:217], v[42:45]
	v_mfma_f32_16x16x32_bf16 v[34:37], v[150:153], v[214:217], v[34:37]
	v_mfma_f32_16x16x32_bf16 v[26:29], v[142:145], v[226:229], v[26:29]
	v_mfma_f32_16x16x32_bf16 v[18:21], v[150:153], v[226:229], v[18:21]
	v_mfma_f32_16x16x32_bf16 v[10:13], v[142:145], v[234:237], v[10:13]
	v_mfma_f32_16x16x32_bf16 v[4:7], v[150:153], v[234:237], v[4:7]
	v_mfma_f32_16x16x32_bf16 v[58:61], v[146:149], v[210:213], v[58:61]
	v_mfma_f32_16x16x32_bf16 v[50:53], v[172:175], v[210:213], v[50:53]
	v_mfma_f32_16x16x32_bf16 v[42:45], v[146:149], v[218:221], v[42:45]
	v_mfma_f32_16x16x32_bf16 v[34:37], v[172:175], v[218:221], v[34:37]
	v_mfma_f32_16x16x32_bf16 v[26:29], v[146:149], v[230:233], v[26:29]
	v_mfma_f32_16x16x32_bf16 v[18:21], v[172:175], v[230:233], v[18:21]
	v_mfma_f32_16x16x32_bf16 v[10:13], v[146:149], v[238:241], v[10:13]
	v_mfma_f32_16x16x32_bf16 v[4:7], v[172:175], v[238:241], v[4:7]
	s_setprio 0
	s_setprio 1
	v_mfma_f32_16x16x32_bf16 v[62:65], v[190:193], v[206:209], v[62:65]
	v_mfma_f32_16x16x32_bf16 v[54:57], v[198:201], v[206:209], v[54:57]
	v_mfma_f32_16x16x32_bf16 v[46:49], v[190:193], v[214:217], v[46:49]
	v_mfma_f32_16x16x32_bf16 v[38:41], v[198:201], v[214:217], v[38:41]
	v_mfma_f32_16x16x32_bf16 v[30:33], v[190:193], v[226:229], v[30:33]
	v_mfma_f32_16x16x32_bf16 v[22:25], v[198:201], v[226:229], v[22:25]
	v_mfma_f32_16x16x32_bf16 v[14:17], v[190:193], v[234:237], v[14:17]
	v_mfma_f32_16x16x32_bf16 v[0:3], v[198:201], v[234:237], v[0:3]
	v_mfma_f32_16x16x32_bf16 v[62:65], v[194:197], v[210:213], v[62:65]
	v_mfma_f32_16x16x32_bf16 v[54:57], v[202:205], v[210:213], v[54:57]
	v_mfma_f32_16x16x32_bf16 v[46:49], v[194:197], v[218:221], v[46:49]
	v_mfma_f32_16x16x32_bf16 v[38:41], v[202:205], v[218:221], v[38:41]
	v_mfma_f32_16x16x32_bf16 v[30:33], v[194:197], v[230:233], v[30:33]
	v_mfma_f32_16x16x32_bf16 v[22:25], v[202:205], v[230:233], v[22:25]
	v_mfma_f32_16x16x32_bf16 v[14:17], v[194:197], v[238:241], v[14:17]
	v_mfma_f32_16x16x32_bf16 v[0:3], v[202:205], v[238:241], v[0:3]
	s_setprio 0
	s_barrier
	s_add_i32 s53, 0, 0x18000
	v_add_u32_e32 v8, s53, v178
	s_add_i32 s54, 0, 0x1c000
	ds_read_b128 v[142:145], v8
	ds_read_b128 v[146:149], v8 offset:1024
	ds_read_b128 v[150:153], v8 offset:2048
	ds_read_b128 v[172:175], v8 offset:3072
	v_add_u32_e32 v8, s54, v178
	ds_read_b128 v[190:193], v8
	ds_read_b128 v[194:197], v8 offset:1024
	ds_read_b128 v[198:201], v8 offset:2048
	ds_read_b128 v[202:205], v8 offset:3072
	s_add_u32 s40, s40, 0x80000
	s_addc_u32 s41, s41, 0
	s_mov_b32 m0, s43
	v_lshl_add_u64 v[246:247], s[40:41], 0, v[136:137]
	ds_read_b128 v[206:209], v180 offset:32768
	ds_read_b128 v[210:213], v180 offset:33792
	ds_read_b128 v[214:217], v180 offset:34816
	ds_read_b128 v[218:221], v180 offset:35840
	ds_read_b128 v[226:229], v180 offset:36864
	ds_read_b128 v[230:233], v180 offset:37888
	ds_read_b128 v[234:237], v180 offset:38912
	ds_read_b128 v[238:241], v180 offset:39936
	global_load_lds_dwordx4 v[246:247], off
	v_lshl_add_u64 v[246:247], s[40:41], 0, v[132:133]
	s_mov_b32 m0, s44
	s_nop 0
	global_load_lds_dwordx4 v[246:247], off
	s_waitcnt vmcnt(8)
	s_waitcnt lgkmcnt(0)
	s_barrier
	s_setprio 1
	s_waitcnt lgkmcnt(0)
	v_mfma_f32_16x16x32_bf16 v[126:129], v[142:145], v[206:209], v[126:129]
	v_mfma_f32_16x16x32_bf16 v[118:121], v[150:153], v[206:209], v[118:121]
	v_mfma_f32_16x16x32_bf16 v[106:109], v[142:145], v[214:217], v[106:109]
	v_mfma_f32_16x16x32_bf16 v[98:101], v[150:153], v[214:217], v[98:101]
	v_mfma_f32_16x16x32_bf16 v[90:93], v[142:145], v[226:229], v[90:93]
	v_mfma_f32_16x16x32_bf16 v[82:85], v[150:153], v[226:229], v[82:85]
	v_mfma_f32_16x16x32_bf16 v[74:77], v[142:145], v[234:237], v[74:77]
	v_mfma_f32_16x16x32_bf16 v[66:69], v[150:153], v[234:237], v[66:69]
	v_mfma_f32_16x16x32_bf16 v[126:129], v[146:149], v[210:213], v[126:129]
	v_mfma_f32_16x16x32_bf16 v[118:121], v[172:175], v[210:213], v[118:121]
	v_mfma_f32_16x16x32_bf16 v[106:109], v[146:149], v[218:221], v[106:109]
	v_mfma_f32_16x16x32_bf16 v[98:101], v[172:175], v[218:221], v[98:101]
	v_mfma_f32_16x16x32_bf16 v[90:93], v[146:149], v[230:233], v[90:93]
	v_mfma_f32_16x16x32_bf16 v[82:85], v[172:175], v[230:233], v[82:85]
	v_mfma_f32_16x16x32_bf16 v[74:77], v[146:149], v[238:241], v[74:77]
	v_mfma_f32_16x16x32_bf16 v[66:69], v[172:175], v[238:241], v[66:69]
	s_setprio 0
	s_setprio 1
	v_mfma_f32_16x16x32_bf16 v[122:125], v[190:193], v[206:209], v[122:125]
	v_mfma_f32_16x16x32_bf16 v[114:117], v[198:201], v[206:209], v[114:117]
	v_mfma_f32_16x16x32_bf16 v[110:113], v[190:193], v[214:217], v[110:113]
	v_mfma_f32_16x16x32_bf16 v[102:105], v[198:201], v[214:217], v[102:105]
	v_mfma_f32_16x16x32_bf16 v[94:97], v[190:193], v[226:229], v[94:97]
	v_mfma_f32_16x16x32_bf16 v[86:89], v[198:201], v[226:229], v[86:89]
	v_mfma_f32_16x16x32_bf16 v[78:81], v[190:193], v[234:237], v[78:81]
	v_mfma_f32_16x16x32_bf16 v[70:73], v[198:201], v[234:237], v[70:73]
	v_mfma_f32_16x16x32_bf16 v[122:125], v[194:197], v[210:213], v[122:125]
	v_mfma_f32_16x16x32_bf16 v[114:117], v[202:205], v[210:213], v[114:117]
	v_mfma_f32_16x16x32_bf16 v[110:113], v[194:197], v[218:221], v[110:113]
	v_mfma_f32_16x16x32_bf16 v[102:105], v[202:205], v[218:221], v[102:105]
	v_mfma_f32_16x16x32_bf16 v[94:97], v[194:197], v[230:233], v[94:97]
	v_mfma_f32_16x16x32_bf16 v[86:89], v[202:205], v[230:233], v[86:89]
	v_mfma_f32_16x16x32_bf16 v[78:81], v[194:197], v[238:241], v[78:81]
	v_mfma_f32_16x16x32_bf16 v[70:73], v[202:205], v[238:241], v[70:73]
	s_setprio 0
	s_barrier
	s_add_i32 s40, s53, s8
	v_lshl_add_u64 v[176:177], v[176:177], 0, s[94:95]
	s_mov_b32 m0, s40
	ds_read_b128 v[206:209], v180 offset:49152
	ds_read_b128 v[210:213], v180 offset:50176
	ds_read_b128 v[214:217], v180 offset:51200
	ds_read_b128 v[218:221], v180 offset:52224
	ds_read_b128 v[226:229], v180 offset:53248
	ds_read_b128 v[230:233], v180 offset:54272
	ds_read_b128 v[234:237], v180 offset:55296
	ds_read_b128 v[238:241], v180 offset:56320
	global_load_lds_dwordx4 v[176:177], off
	s_add_i32 m0, s40, 0x2000
	s_add_u32 s4, s4, 0x80080
	v_lshl_add_u64 v[176:177], v[222:223], 0, s[94:95]
	s_addc_u32 s5, s5, 0
	s_add_i32 s40, s54, s8
	global_load_lds_dwordx4 v[176:177], off
	v_lshl_add_u64 v[176:177], s[4:5], 0, v[134:135]
	s_mov_b32 m0, s40
	s_nop 0
	global_load_lds_dwordx4 v[176:177], off
	v_lshl_add_u64 v[176:177], s[4:5], 0, v[130:131]
	s_add_i32 m0, s40, 0x2000
	s_nop 0
	global_load_lds_dwordx4 v[176:177], off
	v_lshl_add_u64 v[176:177], v[242:243], 0, s[94:95]
	s_mov_b32 m0, s45
	s_nop 0
	global_load_lds_dwordx4 v[176:177], off
	v_lshl_add_u64 v[176:177], v[244:245], 0, s[94:95]
	s_mov_b32 m0, s46
	s_nop 0
	global_load_lds_dwordx4 v[176:177], off
	s_waitcnt vmcnt(8)
	s_waitcnt lgkmcnt(0)
	s_barrier
	s_setprio 1
	s_waitcnt lgkmcnt(0)
	v_mfma_f32_16x16x32_bf16 v[58:61], v[142:145], v[206:209], v[58:61]
	v_mfma_f32_16x16x32_bf16 v[50:53], v[150:153], v[206:209], v[50:53]
	v_mfma_f32_16x16x32_bf16 v[42:45], v[142:145], v[214:217], v[42:45]
	v_mfma_f32_16x16x32_bf16 v[34:37], v[150:153], v[214:217], v[34:37]
	v_mfma_f32_16x16x32_bf16 v[26:29], v[142:145], v[226:229], v[26:29]
	v_mfma_f32_16x16x32_bf16 v[18:21], v[150:153], v[226:229], v[18:21]
	v_mfma_f32_16x16x32_bf16 v[10:13], v[142:145], v[234:237], v[10:13]
	v_mfma_f32_16x16x32_bf16 v[4:7], v[150:153], v[234:237], v[4:7]
	v_mfma_f32_16x16x32_bf16 v[58:61], v[146:149], v[210:213], v[58:61]
	v_mfma_f32_16x16x32_bf16 v[50:53], v[172:175], v[210:213], v[50:53]
	v_mfma_f32_16x16x32_bf16 v[42:45], v[146:149], v[218:221], v[42:45]
	v_mfma_f32_16x16x32_bf16 v[34:37], v[172:175], v[218:221], v[34:37]
	v_mfma_f32_16x16x32_bf16 v[26:29], v[146:149], v[230:233], v[26:29]
	v_mfma_f32_16x16x32_bf16 v[18:21], v[172:175], v[230:233], v[18:21]
	v_mfma_f32_16x16x32_bf16 v[10:13], v[146:149], v[238:241], v[10:13]
	v_mfma_f32_16x16x32_bf16 v[4:7], v[172:175], v[238:241], v[4:7]
	s_setprio 0
	s_setprio 1
	v_mfma_f32_16x16x32_bf16 v[62:65], v[190:193], v[206:209], v[62:65]
	v_mfma_f32_16x16x32_bf16 v[54:57], v[198:201], v[206:209], v[54:57]
	v_mfma_f32_16x16x32_bf16 v[46:49], v[190:193], v[214:217], v[46:49]
	v_mfma_f32_16x16x32_bf16 v[38:41], v[198:201], v[214:217], v[38:41]
	v_mfma_f32_16x16x32_bf16 v[30:33], v[190:193], v[226:229], v[30:33]
	v_mfma_f32_16x16x32_bf16 v[22:25], v[198:201], v[226:229], v[22:25]
	v_mfma_f32_16x16x32_bf16 v[14:17], v[190:193], v[234:237], v[14:17]
	v_mfma_f32_16x16x32_bf16 v[0:3], v[198:201], v[234:237], v[0:3]
	v_mfma_f32_16x16x32_bf16 v[62:65], v[194:197], v[210:213], v[62:65]
	v_mfma_f32_16x16x32_bf16 v[54:57], v[202:205], v[210:213], v[54:57]
	v_mfma_f32_16x16x32_bf16 v[46:49], v[194:197], v[218:221], v[46:49]
	v_mfma_f32_16x16x32_bf16 v[38:41], v[202:205], v[218:221], v[38:41]
	v_mfma_f32_16x16x32_bf16 v[30:33], v[194:197], v[230:233], v[30:33]
	v_mfma_f32_16x16x32_bf16 v[22:25], v[202:205], v[230:233], v[22:25]
	v_mfma_f32_16x16x32_bf16 v[14:17], v[194:197], v[238:241], v[14:17]
	v_mfma_f32_16x16x32_bf16 v[0:3], v[202:205], v[238:241], v[0:3]
	s_setprio 0
	s_barrier
	s_add_i32 s52, s52, 2
	s_add_u32 s50, s50, 0x100
	s_addc_u32 s51, s51, 0
	s_add_u32 s36, s36, 0x100
	s_addc_u32 s37, s37, 0
	s_cmp_gt_u32 s52, 29
	s_cbranch_scc0 .LBB0_943
	s_branch .Lgu_join
.Lgu_x:
	s_add_u32 s4, s36, 0xfff80080
	s_addc_u32 s5, s37, -1
	s_add_i32 s53, 0, 0x10000
	s_cmp_eq_u32 s52, 28
	s_cselect_b32 s41, s17, s5
	s_cselect_b32 s40, s27, s4
	v_add_u32_e32 v8, s53, v178
	s_cselect_b32 s5, s25, s51
	s_cselect_b32 s4, s49, s50
	s_add_i32 s56, 0, 0x14000
	ds_read_b128 v[142:145], v8
	ds_read_b128 v[146:149], v8 offset:1024
	ds_read_b128 v[150:153], v8 offset:2048
	ds_read_b128 v[172:175], v8 offset:3072
	v_add_u32_e32 v8, s56, v178
	ds_read_b128 v[190:193], v8
	ds_read_b128 v[194:197], v8 offset:1024
	ds_read_b128 v[198:201], v8 offset:2048
	ds_read_b128 v[202:205], v8 offset:3072
	v_lshl_add_u64 v[176:177], s[36:37], 0, v[140:141]
	s_add_i32 m0, s35, 0xc000
	ds_read_b128 v[206:209], v180
	ds_read_b128 v[210:213], v180 offset:1024
	ds_read_b128 v[214:217], v180 offset:2048
	ds_read_b128 v[218:221], v180 offset:3072
	ds_read_b128 v[226:229], v180 offset:4096
	ds_read_b128 v[230:233], v180 offset:5120
	ds_read_b128 v[234:237], v180 offset:6144
	ds_read_b128 v[238:241], v180 offset:7168
	global_load_lds_dwordx4 v[176:177], off
	v_lshl_add_u64 v[176:177], s[36:37], 0, v[138:139]
	s_add_i32 m0, s35, 0xe000
	s_nop 0
	global_load_lds_dwordx4 v[176:177], off
	s_waitcnt lgkmcnt(0)
	s_barrier
	s_setprio 1
	s_waitcnt lgkmcnt(0)
	v_mfma_f32_16x16x32_bf16 v[126:129], v[142:145], v[206:209], v[126:129]
	v_mfma_f32_16x16x32_bf16 v[118:121], v[150:153], v[206:209], v[118:121]
	v_mfma_f32_16x16x32_bf16 v[106:109], v[142:145], v[214:217], v[106:109]
	v_mfma_f32_16x16x32_bf16 v[98:101], v[150:153], v[214:217], v[98:101]
	v_mfma_f32_16x16x32_bf16 v[90:93], v[142:145], v[226:229], v[90:93]
	v_mfma_f32_16x16x32_bf16 v[82:85], v[150:153], v[226:229], v[82:85]
	v_mfma_f32_16x16x32_bf16 v[74:77], v[142:145], v[234:237], v[74:77]
	v_mfma_f32_16x16x32_bf16 v[66:69], v[150:153], v[234:237], v[66:69]
	v_mfma_f32_16x16x32_bf16 v[126:129], v[146:149], v[210:213], v[126:129]
	v_mfma_f32_16x16x32_bf16 v[118:121], v[172:175], v[210:213], v[118:121]
	v_mfma_f32_16x16x32_bf16 v[106:109], v[146:149], v[218:221], v[106:109]
	v_mfma_f32_16x16x32_bf16 v[98:101], v[172:175], v[218:221], v[98:101]
	v_mfma_f32_16x16x32_bf16 v[90:93], v[146:149], v[230:233], v[90:93]
	v_mfma_f32_16x16x32_bf16 v[82:85], v[172:175], v[230:233], v[82:85]
	v_mfma_f32_16x16x32_bf16 v[74:77], v[146:149], v[238:241], v[74:77]
	v_mfma_f32_16x16x32_bf16 v[66:69], v[172:175], v[238:241], v[66:69]
	s_setprio 0
	s_setprio 1
	v_mfma_f32_16x16x32_bf16 v[122:125], v[190:193], v[206:209], v[122:125]
	v_mfma_f32_16x16x32_bf16 v[114:117], v[198:201], v[206:209], v[114:117]
	v_mfma_f32_16x16x32_bf16 v[110:113], v[190:193], v[214:217], v[110:113]
	v_mfma_f32_16x16x32_bf16 v[102:105], v[198:201], v[214:217], v[102:105]
	v_mfma_f32_16x16x32_bf16 v[94:97], v[190:193], v[226:229], v[94:97]
	v_mfma_f32_16x16x32_bf16 v[86:89], v[198:201], v[226:229], v[86:89]
	v_mfma_f32_16x16x32_bf16 v[78:81], v[190:193], v[234:237], v[78:81]
	v_mfma_f32_16x16x32_bf16 v[70:73], v[198:201], v[234:237], v[70:73]
	v_mfma_f32_16x16x32_bf16 v[122:125], v[194:197], v[210:213], v[122:125]
	v_mfma_f32_16x16x32_bf16 v[114:117], v[202:205], v[210:213], v[114:117]
	v_mfma_f32_16x16x32_bf16 v[110:113], v[194:197], v[218:221], v[110:113]
	v_mfma_f32_16x16x32_bf16 v[102:105], v[202:205], v[218:221], v[102:105]
	v_mfma_f32_16x16x32_bf16 v[94:97], v[194:197], v[230:233], v[94:97]
	v_mfma_f32_16x16x32_bf16 v[86:89], v[202:205], v[230:233], v[86:89]
	v_mfma_f32_16x16x32_bf16 v[78:81], v[194:197], v[238:241], v[78:81]
	v_mfma_f32_16x16x32_bf16 v[70:73], v[202:205], v[238:241], v[70:73]
	s_setprio 0
	s_waitcnt vmcnt(8)
	s_barrier
	s_add_i32 s53, s53, s8
	v_lshl_add_u64 v[176:177], s[4:5], 0, v[134:135]
	s_mov_b32 m0, s53
	ds_read_b128 v[206:209], v180 offset:16384
	ds_read_b128 v[210:213], v180 offset:17408
	ds_read_b128 v[214:217], v180 offset:18432
	ds_read_b128 v[218:221], v180 offset:19456
	ds_read_b128 v[226:229], v180 offset:20480
	ds_read_b128 v[230:233], v180 offset:21504
	ds_read_b128 v[234:237], v180 offset:22528
	ds_read_b128 v[238:241], v180 offset:23552
	global_load_lds_dwordx4 v[176:177], off
	s_add_i32 m0, s53, 0x2000
	s_add_u32 s54, s4, 0x80000
	v_lshl_add_u64 v[222:223], s[4:5], 0, v[130:131]
	s_addc_u32 s55, s5, 0
	s_add_i32 s53, s56, s8
	global_load_lds_dwordx4 v[222:223], off
	v_lshl_add_u64 v[242:243], s[54:55], 0, v[134:135]
	s_mov_b32 m0, s53
	v_lshl_add_u64 v[244:245], s[40:41], 0, v[132:133]
	global_load_lds_dwordx4 v[242:243], off
	v_lshl_add_u64 v[242:243], s[54:55], 0, v[130:131]
	s_add_i32 m0, s53, 0x2000
	s_nop 0
	global_load_lds_dwordx4 v[242:243], off
	v_lshl_add_u64 v[242:243], s[40:41], 0, v[136:137]
	s_mov_b32 m0, s35
	s_nop 0
	global_load_lds_dwordx4 v[242:243], off
	s_mov_b32 m0, s42
	s_nop 0
	global_load_lds_dwordx4 v[244:245], off
	s_waitcnt lgkmcnt(0)
	s_barrier
	s_setprio 1
	s_waitcnt lgkmcnt(0)
	v_mfma_f32_16x16x32_bf16 v[58:61], v[142:145], v[206:209], v[58:61]
	v_mfma_f32_16x16x32_bf16 v[50:53], v[150:153], v[206:209], v[50:53]
	v_mfma_f32_16x16x32_bf16 v[42:45], v[142:145], v[214:217], v[42:45]
	v_mfma_f32_16x16x32_bf16 v[34:37], v[150:153], v[214:217], v[34:37]
	v_mfma_f32_16x16x32_bf16 v[26:29], v[142:145], v[226:229], v[26:29]
	v_mfma_f32_16x16x32_bf16 v[18:21], v[150:153], v[226:229], v[18:21]
	v_mfma_f32_16x16x32_bf16 v[10:13], v[142:145], v[234:237], v[10:13]
	v_mfma_f32_16x16x32_bf16 v[4:7], v[150:153], v[234:237], v[4:7]
	v_mfma_f32_16x16x32_bf16 v[58:61], v[146:149], v[210:213], v[58:61]
	v_mfma_f32_16x16x32_bf16 v[50:53], v[172:175], v[210:213], v[50:53]
	v_mfma_f32_16x16x32_bf16 v[42:45], v[146:149], v[218:221], v[42:45]
	v_mfma_f32_16x16x32_bf16 v[34:37], v[172:175], v[218:221], v[34:37]
	v_mfma_f32_16x16x32_bf16 v[26:29], v[146:149], v[230:233], v[26:29]
	v_mfma_f32_16x16x32_bf16 v[18:21], v[172:175], v[230:233], v[18:21]
	v_mfma_f32_16x16x32_bf16 v[10:13], v[146:149], v[238:241], v[10:13]
	v_mfma_f32_16x16x32_bf16 v[4:7], v[172:175], v[238:241], v[4:7]
	s_setprio 0
	s_setprio 1
	v_mfma_f32_16x16x32_bf16 v[62:65], v[190:193], v[206:209], v[62:65]
	v_mfma_f32_16x16x32_bf16 v[54:57], v[198:201], v[206:209], v[54:57]
	v_mfma_f32_16x16x32_bf16 v[46:49], v[190:193], v[214:217], v[46:49]
	v_mfma_f32_16x16x32_bf16 v[38:41], v[198:201], v[214:217], v[38:41]
	v_mfma_f32_16x16x32_bf16 v[30:33], v[190:193], v[226:229], v[30:33]
	v_mfma_f32_16x16x32_bf16 v[22:25], v[198:201], v[226:229], v[22:25]
	v_mfma_f32_16x16x32_bf16 v[14:17], v[190:193], v[234:237], v[14:17]
	v_mfma_f32_16x16x32_bf16 v[0:3], v[198:201], v[234:237], v[0:3]
	v_mfma_f32_16x16x32_bf16 v[62:65], v[194:197], v[210:213], v[62:65]
	v_mfma_f32_16x16x32_bf16 v[54:57], v[202:205], v[210:213], v[54:57]
	v_mfma_f32_16x16x32_bf16 v[46:49], v[194:197], v[218:221], v[46:49]
	v_mfma_f32_16x16x32_bf16 v[38:41], v[202:205], v[218:221], v[38:41]
	v_mfma_f32_16x16x32_bf16 v[30:33], v[194:197], v[230:233], v[30:33]
	v_mfma_f32_16x16x32_bf16 v[22:25], v[202:205], v[230:233], v[22:25]
	v_mfma_f32_16x16x32_bf16 v[14:17], v[194:197], v[238:241], v[14:17]
	v_mfma_f32_16x16x32_bf16 v[0:3], v[202:205], v[238:241], v[0:3]
	s_setprio 0
	s_waitcnt vmcnt(8)
	s_barrier
	s_add_i32 s53, 0, 0x18000
	v_add_u32_e32 v8, s53, v178
	s_add_i32 s54, 0, 0x1c000
	ds_read_b128 v[142:145], v8
	ds_read_b128 v[146:149], v8 offset:1024
	ds_read_b128 v[150:153], v8 offset:2048
	ds_read_b128 v[172:175], v8 offset:3072
	v_add_u32_e32 v8, s54, v178
	ds_read_b128 v[190:193], v8
	ds_read_b128 v[194:197], v8 offset:1024
	ds_read_b128 v[198:201], v8 offset:2048
	ds_read_b128 v[202:205], v8 offset:3072
	s_add_u32 s40, s40, 0x80000
	s_addc_u32 s41, s41, 0
	s_mov_b32 m0, s43
	v_lshl_add_u64 v[246:247], s[40:41], 0, v[136:137]
	ds_read_b128 v[206:209], v180 offset:32768
	ds_read_b128 v[210:213], v180 offset:33792
	ds_read_b128 v[214:217], v180 offset:34816
	ds_read_b128 v[218:221], v180 offset:35840
	ds_read_b128 v[226:229], v180 offset:36864
	ds_read_b128 v[230:233], v180 offset:37888
	ds_read_b128 v[234:237], v180 offset:38912
	ds_read_b128 v[238:241], v180 offset:39936
	global_load_lds_dwordx4 v[246:247], off
	v_lshl_add_u64 v[246:247], s[40:41], 0, v[132:133]
	s_mov_b32 m0, s44
	s_nop 0
	global_load_lds_dwordx4 v[246:247], off
	s_waitcnt lgkmcnt(0)
	s_barrier
	s_setprio 1
	s_waitcnt lgkmcnt(0)
	v_mfma_f32_16x16x32_bf16 v[126:129], v[142:145], v[206:209], v[126:129]
	v_mfma_f32_16x16x32_bf16 v[118:121], v[150:153], v[206:209], v[118:121]
	v_mfma_f32_16x16x32_bf16 v[106:109], v[142:145], v[214:217], v[106:109]
	v_mfma_f32_16x16x32_bf16 v[98:101], v[150:153], v[214:217], v[98:101]
	v_mfma_f32_16x16x32_bf16 v[90:93], v[142:145], v[226:229], v[90:93]
	v_mfma_f32_16x16x32_bf16 v[82:85], v[150:153], v[226:229], v[82:85]
	v_mfma_f32_16x16x32_bf16 v[74:77], v[142:145], v[234:237], v[74:77]
	v_mfma_f32_16x16x32_bf16 v[66:69], v[150:153], v[234:237], v[66:69]
	v_mfma_f32_16x16x32_bf16 v[126:129], v[146:149], v[210:213], v[126:129]
	v_mfma_f32_16x16x32_bf16 v[118:121], v[172:175], v[210:213], v[118:121]
	v_mfma_f32_16x16x32_bf16 v[106:109], v[146:149], v[218:221], v[106:109]
	v_mfma_f32_16x16x32_bf16 v[98:101], v[172:175], v[218:221], v[98:101]
	v_mfma_f32_16x16x32_bf16 v[90:93], v[146:149], v[230:233], v[90:93]
	v_mfma_f32_16x16x32_bf16 v[82:85], v[172:175], v[230:233], v[82:85]
	v_mfma_f32_16x16x32_bf16 v[74:77], v[146:149], v[238:241], v[74:77]
	v_mfma_f32_16x16x32_bf16 v[66:69], v[172:175], v[238:241], v[66:69]
	s_setprio 0
	s_setprio 1
	v_mfma_f32_16x16x32_bf16 v[122:125], v[190:193], v[206:209], v[122:125]
	v_mfma_f32_16x16x32_bf16 v[114:117], v[198:201], v[206:209], v[114:117]
	v_mfma_f32_16x16x32_bf16 v[110:113], v[190:193], v[214:217], v[110:113]
	v_mfma_f32_16x16x32_bf16 v[102:105], v[198:201], v[214:217], v[102:105]
	v_mfma_f32_16x16x32_bf16 v[94:97], v[190:193], v[226:229], v[94:97]
	v_mfma_f32_16x16x32_bf16 v[86:89], v[198:201], v[226:229], v[86:89]
	v_mfma_f32_16x16x32_bf16 v[78:81], v[190:193], v[234:237], v[78:81]
	v_mfma_f32_16x16x32_bf16 v[70:73], v[198:201], v[234:237], v[70:73]
	v_mfma_f32_16x16x32_bf16 v[122:125], v[194:197], v[210:213], v[122:125]
	v_mfma_f32_16x16x32_bf16 v[114:117], v[202:205], v[210:213], v[114:117]
	v_mfma_f32_16x16x32_bf16 v[110:113], v[194:197], v[218:221], v[110:113]
	v_mfma_f32_16x16x32_bf16 v[102:105], v[202:205], v[218:221], v[102:105]
	v_mfma_f32_16x16x32_bf16 v[94:97], v[194:197], v[230:233], v[94:97]
	v_mfma_f32_16x16x32_bf16 v[86:89], v[202:205], v[230:233], v[86:89]
	v_mfma_f32_16x16x32_bf16 v[78:81], v[194:197], v[238:241], v[78:81]
	v_mfma_f32_16x16x32_bf16 v[70:73], v[202:205], v[238:241], v[70:73]
	s_setprio 0
	s_waitcnt vmcnt(8)
	s_barrier
	s_add_i32 s40, s53, s8
	v_lshl_add_u64 v[176:177], v[176:177], 0, s[94:95]
	s_mov_b32 m0, s40
	ds_read_b128 v[206:209], v180 offset:49152
	ds_read_b128 v[210:213], v180 offset:50176
	ds_read_b128 v[214:217], v180 offset:51200
	ds_read_b128 v[218:221], v180 offset:52224
	ds_read_b128 v[226:229], v180 offset:53248
	ds_read_b128 v[230:233], v180 offset:54272
	ds_read_b128 v[234:237], v180 offset:55296
	ds_read_b128 v[238:241], v180 offset:56320
	global_load_lds_dwordx4 v[176:177], off
	s_add_i32 m0, s40, 0x2000
	s_add_u32 s4, s4, 0x80080
	v_lshl_add_u64 v[176:177], v[222:223], 0, s[94:95]
	s_addc_u32 s5, s5, 0
	s_add_i32 s40, s54, s8
	global_load_lds_dwordx4 v[176:177], off
	v_lshl_add_u64 v[176:177], s[4:5], 0, v[134:135]
	s_mov_b32 m0, s40
	s_nop 0
	global_load_lds_dwordx4 v[176:177], off
	v_lshl_add_u64 v[176:177], s[4:5], 0, v[130:131]
	s_add_i32 m0, s40, 0x2000
	s_nop 0
	global_load_lds_dwordx4 v[176:177], off
	v_lshl_add_u64 v[176:177], v[242:243], 0, s[94:95]
	s_mov_b32 m0, s45
	s_nop 0
	global_load_lds_dwordx4 v[176:177], off
	v_lshl_add_u64 v[176:177], v[244:245], 0, s[94:95]
	s_mov_b32 m0, s46
	s_nop 0
	global_load_lds_dwordx4 v[176:177], off
	s_waitcnt lgkmcnt(0)
	s_barrier
	s_setprio 1
	s_waitcnt lgkmcnt(0)
	v_mfma_f32_16x16x32_bf16 v[58:61], v[142:145], v[206:209], v[58:61]
	v_mfma_f32_16x16x32_bf16 v[50:53], v[150:153], v[206:209], v[50:53]
	v_mfma_f32_16x16x32_bf16 v[42:45], v[142:145], v[214:217], v[42:45]
	v_mfma_f32_16x16x32_bf16 v[34:37], v[150:153], v[214:217], v[34:37]
	v_mfma_f32_16x16x32_bf16 v[26:29], v[142:145], v[226:229], v[26:29]
	v_mfma_f32_16x16x32_bf16 v[18:21], v[150:153], v[226:229], v[18:21]
	v_mfma_f32_16x16x32_bf16 v[10:13], v[142:145], v[234:237], v[10:13]
	v_mfma_f32_16x16x32_bf16 v[4:7], v[150:153], v[234:237], v[4:7]
	v_mfma_f32_16x16x32_bf16 v[58:61], v[146:149], v[210:213], v[58:61]
	v_mfma_f32_16x16x32_bf16 v[50:53], v[172:175], v[210:213], v[50:53]
	v_mfma_f32_16x16x32_bf16 v[42:45], v[146:149], v[218:221], v[42:45]
	v_mfma_f32_16x16x32_bf16 v[34:37], v[172:175], v[218:221], v[34:37]
	v_mfma_f32_16x16x32_bf16 v[26:29], v[146:149], v[230:233], v[26:29]
	v_mfma_f32_16x16x32_bf16 v[18:21], v[172:175], v[230:233], v[18:21]
	v_mfma_f32_16x16x32_bf16 v[10:13], v[146:149], v[238:241], v[10:13]
	v_mfma_f32_16x16x32_bf16 v[4:7], v[172:175], v[238:241], v[4:7]
	s_setprio 0
	s_setprio 1
	v_mfma_f32_16x16x32_bf16 v[62:65], v[190:193], v[206:209], v[62:65]
	v_mfma_f32_16x16x32_bf16 v[54:57], v[198:201], v[206:209], v[54:57]
	v_mfma_f32_16x16x32_bf16 v[46:49], v[190:193], v[214:217], v[46:49]
	v_mfma_f32_16x16x32_bf16 v[38:41], v[198:201], v[214:217], v[38:41]
	v_mfma_f32_16x16x32_bf16 v[30:33], v[190:193], v[226:229], v[30:33]
	v_mfma_f32_16x16x32_bf16 v[22:25], v[198:201], v[226:229], v[22:25]
	v_mfma_f32_16x16x32_bf16 v[14:17], v[190:193], v[234:237], v[14:17]
	v_mfma_f32_16x16x32_bf16 v[0:3], v[198:201], v[234:237], v[0:3]
	v_mfma_f32_16x16x32_bf16 v[62:65], v[194:197], v[210:213], v[62:65]
	v_mfma_f32_16x16x32_bf16 v[54:57], v[202:205], v[210:213], v[54:57]
	v_mfma_f32_16x16x32_bf16 v[46:49], v[194:197], v[218:221], v[46:49]
	v_mfma_f32_16x16x32_bf16 v[38:41], v[202:205], v[218:221], v[38:41]
	v_mfma_f32_16x16x32_bf16 v[30:33], v[194:197], v[230:233], v[30:33]
	v_mfma_f32_16x16x32_bf16 v[22:25], v[202:205], v[230:233], v[22:25]
	v_mfma_f32_16x16x32_bf16 v[14:17], v[194:197], v[238:241], v[14:17]
	v_mfma_f32_16x16x32_bf16 v[0:3], v[202:205], v[238:241], v[0:3]
	s_setprio 0
	s_waitcnt vmcnt(8)
	s_barrier
	s_add_i32 s52, s52, 2
	s_add_u32 s50, s50, 0x100
	s_addc_u32 s51, s51, 0
	s_add_u32 s36, s36, 0x100
	s_addc_u32 s37, s37, 0
	s_cmp_gt_u32 s52, 29
	s_cbranch_scc0 .Lgu_x
.Lgu_join:
	s_and_b64 vcc, exec, s[22:23]
	s_cbranch_vccz .LBB0_946
	s_barrier
